# T4 + skinny_mfma x-fragment loads issued up front with counted vmcnt (were 16 serialised round trips)
# speedup vs baseline: 1.0091x; 1.0091x over previous
; #define GAS __attribute__((address_space(1)))
; template <int NB_, int MODE> ...
;     ...
;         const GAS bf16_t* xp = (const GAS bf16_t*)Xb + (size_t)tok * D + wave * 256 + 8 * hi;
;         const GAS bf16_t* wp = (const GAS bf16_t*)Ws + (size_t)c * D + wave * 256 + 8 * hi;
; #pragma unroll
;         for (int s = 0; s < 16; ++s) {
;             const bf16x8 xf = *(const GAS bf16x8*)(xp + 16 * s);
; #pragma unroll
;             for (int nb = 0; nb < NB_; ++nb)
;                 acc[nb] = __builtin_amdgcn_mfma_f32_32x32x16_bf16(*(const GAS bf16x8*)(wp + (size_t)nb * 32 * D + 16 * s), xf, acc[nb], 0, 0, 0);
;         }
;         if (wave != 0) {
; #pragma unroll
;             for (int nb = 0; nb < NB_; ++nb)
; #pragma unroll
;                 for (int r = 0; r < 16; ++r) part[((wave * NB_ + nb) * 16 + r) * 64 + lane] = acc[nb][r];
;         }
.LBB0_173:
	v_lshl_or_b32 v88, s14, 5, v1
	v_ashrrev_i32_e32 v89, 31, v88
	v_lshlrev_b64 v[4:5], 12, v[88:89]
	v_lshl_add_u64 v[94:95], v[84:85], 0, v[4:5]
	global_load_dwordx4 v[120:123], v[94:95], off
	global_load_dwordx4 v[124:127], v[94:95], off offset:32
	global_load_dwordx4 v[128:131], v[94:95], off offset:64
	global_load_dwordx4 v[132:135], v[94:95], off offset:96
	global_load_dwordx4 v[136:139], v[94:95], off offset:128
	global_load_dwordx4 v[140:143], v[94:95], off offset:160
	global_load_dwordx4 v[144:147], v[94:95], off offset:192
	global_load_dwordx4 v[148:151], v[94:95], off offset:224
	global_load_dwordx4 v[152:155], v[94:95], off offset:256
	global_load_dwordx4 v[156:159], v[94:95], off offset:288
	global_load_dwordx4 v[160:163], v[94:95], off offset:320
	global_load_dwordx4 v[164:167], v[94:95], off offset:352
	global_load_dwordx4 v[168:171], v[94:95], off offset:384
	global_load_dwordx4 v[172:175], v[94:95], off offset:416
	global_load_dwordx4 v[176:179], v[94:95], off offset:448
	global_load_dwordx4 v[180:183], v[94:95], off offset:480
	s_waitcnt vmcnt(15)
	v_mfma_f32_32x32x16_bf16 v[4:19], v[76:79], v[120:123], 0
	s_waitcnt vmcnt(14)
	v_mfma_f32_32x32x16_bf16 v[4:19], v[20:23], v[124:127], v[4:19]
	s_waitcnt vmcnt(13)
	v_mfma_f32_32x32x16_bf16 v[4:19], v[24:27], v[128:131], v[4:19]
	s_waitcnt vmcnt(12)
	v_mfma_f32_32x32x16_bf16 v[4:19], v[28:31], v[132:135], v[4:19]
	s_waitcnt vmcnt(11)
	v_mfma_f32_32x32x16_bf16 v[4:19], v[32:35], v[136:139], v[4:19]
	s_waitcnt vmcnt(10)
	v_mfma_f32_32x32x16_bf16 v[4:19], v[36:39], v[140:143], v[4:19]
	s_waitcnt vmcnt(9)
	v_mfma_f32_32x32x16_bf16 v[4:19], v[40:43], v[144:147], v[4:19]
	s_waitcnt vmcnt(8)
	v_mfma_f32_32x32x16_bf16 v[4:19], v[44:47], v[148:151], v[4:19]
	s_waitcnt vmcnt(7)
	v_mfma_f32_32x32x16_bf16 v[4:19], v[48:51], v[152:155], v[4:19]
	s_waitcnt vmcnt(6)
	v_mfma_f32_32x32x16_bf16 v[4:19], v[52:55], v[156:159], v[4:19]
	s_waitcnt vmcnt(5)
	v_mfma_f32_32x32x16_bf16 v[4:19], v[56:59], v[160:163], v[4:19]
	s_waitcnt vmcnt(4)
	v_mfma_f32_32x32x16_bf16 v[4:19], v[60:63], v[164:167], v[4:19]
	s_waitcnt vmcnt(3)
	v_mfma_f32_32x32x16_bf16 v[4:19], v[64:67], v[168:171], v[4:19]
	s_waitcnt vmcnt(2)
	v_mfma_f32_32x32x16_bf16 v[4:19], v[68:71], v[172:175], v[4:19]
	s_waitcnt vmcnt(1)
	v_mfma_f32_32x32x16_bf16 v[4:19], v[72:75], v[176:179], v[4:19]
	s_waitcnt vmcnt(0)
	v_mfma_f32_32x32x16_bf16 v[4:19], v[80:83], v[180:183], v[4:19]
	s_and_saveexec_b64 s[12:13], s[62:63]
	s_xor_b64 s[12:13], exec, s[12:13]
	s_cbranch_execz .LBB0_175
	s_nop 8
	ds_write2st64_b32 v105, v4, v5 offset1:1
	ds_write2st64_b32 v105, v6, v7 offset0:2 offset1:3
	ds_write2st64_b32 v105, v8, v9 offset0:4 offset1:5
	ds_write2st64_b32 v105, v10, v11 offset0:6 offset1:7
	ds_write2st64_b32 v105, v12, v13 offset0:8 offset1:9
	ds_write2st64_b32 v105, v14, v15 offset0:10 offset1:11
	ds_write2st64_b32 v105, v16, v17 offset0:12 offset1:13
	ds_write2st64_b32 v105, v18, v19 offset0:14 offset1:15

; #define GAS __attribute__((address_space(1)))
; template <int NB_, int MODE> ...
;     ...
;         const GAS bf16_t* xp = (const GAS bf16_t*)Xb + (size_t)tok * D + wave * 256 + 8 * hi;
;         const GAS bf16_t* wp = (const GAS bf16_t*)Ws + (size_t)c * D + wave * 256 + 8 * hi;
; #pragma unroll
;         for (int s = 0; s < 16; ++s) {
;             const bf16x8 xf = *(const GAS bf16x8*)(xp + 16 * s);
; #pragma unroll
;             for (int nb = 0; nb < NB_; ++nb)
;                 acc[nb] = __builtin_amdgcn_mfma_f32_32x32x16_bf16(*(const GAS bf16x8*)(wp + (size_t)nb * 32 * D + 16 * s), xf, acc[nb], 0, 0, 0);
;         }
;         if (wave != 0) {
; #pragma unroll
;             for (int nb = 0; nb < NB_; ++nb)
; #pragma unroll
;                 for (int r = 0; r < 16; ++r) part[((wave * NB_ + nb) * 16 + r) * 64 + lane] = acc[nb][r];
;         }
.LBB0_687:
	v_lshl_or_b32 v176, s14, 5, v1
	v_ashrrev_i32_e32 v177, 31, v176
	v_lshlrev_b64 v[4:5], 12, v[176:177]
	v_lshl_add_u64 v[172:173], v[164:165], 0, v[4:5]
	global_load_dwordx4 v[208:211], v[172:173], off
	global_load_dwordx4 v[212:215], v[172:173], off offset:32
	global_load_dwordx4 v[216:219], v[172:173], off offset:64
	global_load_dwordx4 v[220:223], v[172:173], off offset:96
	global_load_dwordx4 v[224:227], v[172:173], off offset:128
	global_load_dwordx4 v[228:231], v[172:173], off offset:160
	global_load_dwordx4 v[232:235], v[172:173], off offset:192
	global_load_dwordx4 v[236:239], v[172:173], off offset:224
	global_load_dwordx4 v[240:243], v[172:173], off offset:256
	global_load_dwordx4 v[244:247], v[172:173], off offset:288
	s_waitcnt vmcnt(9)
	v_mfma_f32_32x32x16_bf16 v[4:19], v[148:151], v[208:211], 0
	v_mfma_f32_32x32x16_bf16 v[20:35], v[36:39], v[208:211], 0
	global_load_dwordx4 v[208:211], v[172:173], off offset:320
	s_waitcnt vmcnt(9)
	v_mfma_f32_32x32x16_bf16 v[4:19], v[44:47], v[212:215], v[4:19]
	v_mfma_f32_32x32x16_bf16 v[20:35], v[40:43], v[212:215], v[20:35]
	global_load_dwordx4 v[212:215], v[172:173], off offset:352
	s_waitcnt vmcnt(9)
	v_mfma_f32_32x32x16_bf16 v[4:19], v[48:51], v[216:219], v[4:19]
	v_mfma_f32_32x32x16_bf16 v[20:35], v[52:55], v[216:219], v[20:35]
	global_load_dwordx4 v[216:219], v[172:173], off offset:384
	s_waitcnt vmcnt(9)
	v_mfma_f32_32x32x16_bf16 v[4:19], v[60:63], v[220:223], v[4:19]
	v_mfma_f32_32x32x16_bf16 v[20:35], v[56:59], v[220:223], v[20:35]
	global_load_dwordx4 v[220:223], v[172:173], off offset:416
	s_waitcnt vmcnt(9)
	v_mfma_f32_32x32x16_bf16 v[4:19], v[64:67], v[224:227], v[4:19]
	v_mfma_f32_32x32x16_bf16 v[20:35], v[68:71], v[224:227], v[20:35]
	global_load_dwordx4 v[224:227], v[172:173], off offset:448
	s_waitcnt vmcnt(9)
	v_mfma_f32_32x32x16_bf16 v[4:19], v[76:79], v[228:231], v[4:19]
	v_mfma_f32_32x32x16_bf16 v[20:35], v[72:75], v[228:231], v[20:35]
	global_load_dwordx4 v[228:231], v[172:173], off offset:480
	s_waitcnt vmcnt(9)
	v_mfma_f32_32x32x16_bf16 v[4:19], v[80:83], v[232:235], v[4:19]
	v_mfma_f32_32x32x16_bf16 v[20:35], v[84:87], v[232:235], v[20:35]
	s_waitcnt vmcnt(8)
	v_mfma_f32_32x32x16_bf16 v[4:19], v[92:95], v[236:239], v[4:19]
	v_mfma_f32_32x32x16_bf16 v[20:35], v[88:91], v[236:239], v[20:35]
	s_waitcnt vmcnt(7)
	v_mfma_f32_32x32x16_bf16 v[4:19], v[96:99], v[240:243], v[4:19]
	v_mfma_f32_32x32x16_bf16 v[20:35], v[100:103], v[240:243], v[20:35]
	s_waitcnt vmcnt(6)
	v_mfma_f32_32x32x16_bf16 v[4:19], v[108:111], v[244:247], v[4:19]
	v_mfma_f32_32x32x16_bf16 v[20:35], v[104:107], v[244:247], v[20:35]
	s_waitcnt vmcnt(5)
	v_mfma_f32_32x32x16_bf16 v[4:19], v[112:115], v[208:211], v[4:19]
	v_mfma_f32_32x32x16_bf16 v[20:35], v[116:119], v[208:211], v[20:35]
	s_waitcnt vmcnt(4)
	v_mfma_f32_32x32x16_bf16 v[4:19], v[124:127], v[212:215], v[4:19]
	v_mfma_f32_32x32x16_bf16 v[20:35], v[120:123], v[212:215], v[20:35]
	s_waitcnt vmcnt(3)
	v_mfma_f32_32x32x16_bf16 v[4:19], v[128:131], v[216:219], v[4:19]
	v_mfma_f32_32x32x16_bf16 v[20:35], v[132:135], v[216:219], v[20:35]
	s_waitcnt vmcnt(2)
	v_mfma_f32_32x32x16_bf16 v[4:19], v[140:143], v[220:223], v[4:19]
	v_mfma_f32_32x32x16_bf16 v[20:35], v[136:139], v[220:223], v[20:35]
	s_waitcnt vmcnt(1)
	v_mfma_f32_32x32x16_bf16 v[4:19], v[144:147], v[224:227], v[4:19]
	v_mfma_f32_32x32x16_bf16 v[20:35], v[156:159], v[224:227], v[20:35]
	s_waitcnt vmcnt(0)
	v_mfma_f32_32x32x16_bf16 v[4:19], v[152:155], v[228:231], v[4:19]
	v_mfma_f32_32x32x16_bf16 v[20:35], v[160:163], v[228:231], v[20:35]
	s_and_saveexec_b64 s[12:13], s[42:43]
	s_cbranch_execz .LBB0_689
	s_nop 8
	ds_write2st64_b32 v187, v4, v5 offset1:1
	ds_write2st64_b32 v187, v6, v7 offset0:2 offset1:3
	ds_write2st64_b32 v187, v8, v9 offset0:4 offset1:5
	ds_write2st64_b32 v187, v10, v11 offset0:6 offset1:7
	ds_write2st64_b32 v187, v12, v13 offset0:8 offset1:9
	ds_write2st64_b32 v187, v14, v15 offset0:10 offset1:11
	ds_write2st64_b32 v187, v16, v17 offset0:12 offset1:13
	ds_write2st64_b32 v187, v18, v19 offset0:14 offset1:15
	ds_write2st64_b32 v187, v20, v21 offset0:16 offset1:17
	ds_write2st64_b32 v187, v22, v23 offset0:18 offset1:19
	ds_write2st64_b32 v187, v24, v25 offset0:20 offset1:21
	ds_write2st64_b32 v187, v26, v27 offset0:22 offset1:23
	ds_write2st64_b32 v187, v28, v29 offset0:24 offset1:25
	ds_write2st64_b32 v187, v30, v31 offset0:26 offset1:27
	ds_write2st64_b32 v187, v32, v33 offset0:28 offset1:29
	ds_write2st64_b32 v187, v34, v35 offset0:30 offset1:31
